# P2b conv pairs redistributed 2,1,1,1,1,1,1,1 over the eight segments (sleep probes showed segments 0-2 critical, the others 8 us slack)
# baseline (speedup 1.0000x reference)
; __global__ void __launch_bounds__(512, 2) hymba_fwd(Params p) {
;     ...
;         for (int u = bx; u < NB * HEADS * NSEG; u += G) { hgrn_seg<true>(p, lds, u >> 5, (u >> 3) & 3, u & 7);
;             const int seg = u & 7, ne = seg < 2 ? 2 : (seg < 6 ? 1 : 0), o0 = (int)((0x88765420u >> (4 * seg)) & 15u);
;             for (int k = 0; k < ne; ++k) conv_pair<16>(p, lds, false, 2 * ((u >> 3) * 8 + o0 + k) + (threadIdx.x >> 8)); }
.LBB0_482:
	s_cmp_lt_u32 s49, 8
	s_cselect_b64 s[46:47], -1, 0
	v_cndmask_b32_e64 v0, 0, 1, s[46:47]
	s_waitcnt lgkmcnt(0)
	s_barrier
	s_cmp_gt_u32 s49, 0
	v_readfirstlane_b32 s4, v0
	s_cselect_b32 s4, s4, 2
	v_readlane_b32 s64, v247, 38
	v_readlane_b32 s52, v247, 36
	s_cmp_eq_u32 s4, 0
	v_readlane_b32 s65, v247, 39
	v_readlane_b32 s66, v247, 40
	v_readlane_b32 s67, v247, 41
	v_readlane_b32 s53, v247, 37
	s_cbranch_scc1 .LBB0_461
	s_lshl_b32 s46, s48, 4
	s_lshl_b32 s47, s48, 8
	s_cmp_eq_u32 s49, 7
	s_cbranch_scc1 .Lp2b_seg6
	s_lshl_b32 s48, s49, 2
	s_lshr_b32 s48, 0x07654320, s48
	s_and_b32 s49, s48, 15
	s_lshl_b32 s48, s4, 5
	s_lshl_b32 s4, s49, 1
	s_add_i32 s4, s4, s46
	v_add_u32_e32 v136, s4, v96
	s_lshl_b32 s4, s49, 5
	s_add_i32 s4, s4, s47
	v_add_u32_e32 v137, s4, v130
	s_mov_b32 s49, 0
	s_branch .LBB0_485
